# LayerNorm of sample rows: split-K plane accumulation loads two planes (16 loads) per round trip with counted waits instead of one load per vmcnt(0); same summation order
# speedup vs baseline: 1.0074x; 1.0074x over previous
.LBB0_297:
	s_add_i32 s46, s19, s26
	s_add_u32 s2, s38, 0x401000
	s_addc_u32 s3, s39, 0
.Lln_pl2:
	s_cmp_lt_u32 s46, 2
	s_cbranch_scc1 .Lln_pl1
	global_load_dwordx4 v[140:143], v72, s[2:3] offset:-4096
	global_load_dwordx4 v[144:147], v72, s[2:3] offset:-3072
	global_load_dwordx4 v[148:151], v72, s[2:3] offset:-2048
	global_load_dwordx4 v[152:155], v72, s[2:3] offset:-1024
	global_load_dwordx4 v[156:159], v72, s[2:3] offset:0
	global_load_dwordx4 v[160:163], v72, s[2:3] offset:1024
	global_load_dwordx4 v[164:167], v72, s[2:3] offset:2048
	global_load_dwordx4 v[168:171], v72, s[2:3] offset:3072
	s_add_u32 s2, s2, 0x400000
	s_addc_u32 s3, s3, 0
	global_load_dwordx4 v[172:175], v72, s[2:3] offset:-4096
	global_load_dwordx4 v[176:179], v72, s[2:3] offset:-3072
	global_load_dwordx4 v[180:183], v72, s[2:3] offset:-2048
	global_load_dwordx4 v[184:187], v72, s[2:3] offset:-1024
	global_load_dwordx4 v[188:191], v72, s[2:3] offset:0
	global_load_dwordx4 v[192:195], v72, s[2:3] offset:1024
	global_load_dwordx4 v[196:199], v72, s[2:3] offset:2048
	global_load_dwordx4 v[220:223], v72, s[2:3] offset:3072
	s_add_u32 s2, s2, 0x400000
	s_addc_u32 s3, s3, 0
	s_add_i32 s46, s46, -2
	s_waitcnt vmcnt(15)
	v_pk_add_f32 v[32:33], v[32:33], v[142:143]
	v_pk_add_f32 v[30:31], v[30:31], v[140:141]
	s_waitcnt vmcnt(14)
	v_pk_add_f32 v[28:29], v[28:29], v[146:147]
	v_pk_add_f32 v[26:27], v[26:27], v[144:145]
	s_waitcnt vmcnt(13)
	v_pk_add_f32 v[24:25], v[24:25], v[150:151]
	v_pk_add_f32 v[22:23], v[22:23], v[148:149]
	s_waitcnt vmcnt(12)
	v_pk_add_f32 v[4:5], v[4:5], v[154:155]
	v_pk_add_f32 v[2:3], v[2:3], v[152:153]
	s_waitcnt vmcnt(11)
	v_pk_add_f32 v[16:17], v[16:17], v[158:159]
	v_pk_add_f32 v[14:15], v[14:15], v[156:157]
	s_waitcnt vmcnt(10)
	v_pk_add_f32 v[8:9], v[8:9], v[162:163]
	v_pk_add_f32 v[6:7], v[6:7], v[160:161]
	s_waitcnt vmcnt(9)
	v_pk_add_f32 v[12:13], v[12:13], v[166:167]
	v_pk_add_f32 v[10:11], v[10:11], v[164:165]
	s_waitcnt vmcnt(8)
	v_pk_add_f32 v[20:21], v[20:21], v[170:171]
	v_pk_add_f32 v[18:19], v[18:19], v[168:169]
	s_waitcnt vmcnt(7)
	v_pk_add_f32 v[32:33], v[32:33], v[174:175]
	v_pk_add_f32 v[30:31], v[30:31], v[172:173]
	s_waitcnt vmcnt(6)
	v_pk_add_f32 v[28:29], v[28:29], v[178:179]
	v_pk_add_f32 v[26:27], v[26:27], v[176:177]
	s_waitcnt vmcnt(5)
	v_pk_add_f32 v[24:25], v[24:25], v[182:183]
	v_pk_add_f32 v[22:23], v[22:23], v[180:181]
	s_waitcnt vmcnt(4)
	v_pk_add_f32 v[4:5], v[4:5], v[186:187]
	v_pk_add_f32 v[2:3], v[2:3], v[184:185]
	s_waitcnt vmcnt(3)
	v_pk_add_f32 v[16:17], v[16:17], v[190:191]
	v_pk_add_f32 v[14:15], v[14:15], v[188:189]
	s_waitcnt vmcnt(2)
	v_pk_add_f32 v[8:9], v[8:9], v[194:195]
	v_pk_add_f32 v[6:7], v[6:7], v[192:193]
	s_waitcnt vmcnt(1)
	v_pk_add_f32 v[12:13], v[12:13], v[198:199]
	v_pk_add_f32 v[10:11], v[10:11], v[196:197]
	s_waitcnt vmcnt(0)
	v_pk_add_f32 v[20:21], v[20:21], v[222:223]
	v_pk_add_f32 v[18:19], v[18:19], v[220:221]
	s_branch .Lln_pl2
.Lln_pl1:
	s_cmp_eq_u32 s46, 0
	s_cbranch_scc1 .LBB0_303
	global_load_dwordx4 v[140:143], v72, s[2:3] offset:-4096
	global_load_dwordx4 v[144:147], v72, s[2:3] offset:-3072
	global_load_dwordx4 v[148:151], v72, s[2:3] offset:-2048
	global_load_dwordx4 v[152:155], v72, s[2:3] offset:-1024
	global_load_dwordx4 v[156:159], v72, s[2:3] offset:0
	global_load_dwordx4 v[160:163], v72, s[2:3] offset:1024
	global_load_dwordx4 v[164:167], v72, s[2:3] offset:2048
	global_load_dwordx4 v[168:171], v72, s[2:3] offset:3072
	s_waitcnt vmcnt(7)
	v_pk_add_f32 v[32:33], v[32:33], v[142:143]
	v_pk_add_f32 v[30:31], v[30:31], v[140:141]
	s_waitcnt vmcnt(6)
	v_pk_add_f32 v[28:29], v[28:29], v[146:147]
	v_pk_add_f32 v[26:27], v[26:27], v[144:145]
	s_waitcnt vmcnt(5)
	v_pk_add_f32 v[24:25], v[24:25], v[150:151]
	v_pk_add_f32 v[22:23], v[22:23], v[148:149]
	s_waitcnt vmcnt(4)
	v_pk_add_f32 v[4:5], v[4:5], v[154:155]
	v_pk_add_f32 v[2:3], v[2:3], v[152:153]
	s_waitcnt vmcnt(3)
	v_pk_add_f32 v[16:17], v[16:17], v[158:159]
	v_pk_add_f32 v[14:15], v[14:15], v[156:157]
	s_waitcnt vmcnt(2)
	v_pk_add_f32 v[8:9], v[8:9], v[162:163]
	v_pk_add_f32 v[6:7], v[6:7], v[160:161]
	s_waitcnt vmcnt(1)
	v_pk_add_f32 v[12:13], v[12:13], v[166:167]
	v_pk_add_f32 v[10:11], v[10:11], v[164:165]
	s_waitcnt vmcnt(0)
	v_pk_add_f32 v[20:21], v[20:21], v[170:171]
	v_pk_add_f32 v[18:19], v[18:19], v[168:169]
